# same as previous version, barrier poll safety cap raised (2^24 polls) so it can only trip on a real deadlock
# speedup vs baseline: 1.0104x; 1.0007x over previous
.Lxb_poll_0:
	global_load_dword v2, v1, s[6:7] offset:1024 sc1
	s_waitcnt vmcnt(0)
	v_readfirstlane_b32 s101, v2
	s_nop 1
	s_cmp_lg_u32 s101, s98
	s_cbranch_scc1 .Lxb_done_0
	s_add_u32 s8, s8, 1
	s_cmp_lt_u32 s8, 0x1000000
	s_cbranch_scc0 .Lxb_done_0
	s_sleep 1
	s_branch .Lxb_poll_0

.Lxb_poll_16:
	global_load_dword v2, v1, s[8:9] offset:1024 sc1
	s_waitcnt vmcnt(0)
	v_readfirstlane_b32 s101, v2
	s_nop 1
	s_cmp_lg_u32 s101, s98
	s_cbranch_scc1 .Lxb_done_16
	s_add_u32 s10, s10, 1
	s_cmp_lt_u32 s10, 0x1000000
	s_cbranch_scc0 .Lxb_done_16
	s_sleep 1
	s_branch .Lxb_poll_16

.Lxb_poll_17:
	global_load_dword v50, v49, s[20:21] offset:1024 sc1
	s_waitcnt vmcnt(0)
	v_readfirstlane_b32 s101, v50
	s_nop 1
	s_cmp_lg_u32 s101, s98
	s_cbranch_scc1 .Lxb_done_17
	s_add_u32 s22, s22, 1
	s_cmp_lt_u32 s22, 0x1000000
	s_cbranch_scc0 .Lxb_done_17
	s_sleep 1
	s_branch .Lxb_poll_17
